# plus: token-wait acquire (buffer_inv) overlapped with GEMM phase setup and weight-tile prefetch; its wait moved before the first activation-tile DMAs behind one extra barrier
# speedup vs baseline: 1.0054x; 1.0043x over previous
.LBB0_129:
	s_or_b64 exec, exec, s[8:9]
	s_waitcnt vmcnt(0)
	buffer_inv sc1
.LBB0_130:
	s_or_b64 exec, exec, s[4:5]

.LBB0_132:
	s_mov_b64 s[12:13], s[88:89]
	v_readlane_b32 s2, v255, 0
	v_readlane_b32 s24, v255, 16
	s_mov_b64 s[0:1], s[94:95]
	v_readlane_b32 s3, v255, 9
	s_add_u32 s0, s12, 0x28600000
	s_addc_u32 s1, s13, 0
	s_sub_i32 s2, s2, s59
	v_mbcnt_lo_u32_b32 v0, -1, 0
	v_mbcnt_hi_u32_b32 v0, -1, v0
	s_mov_b64 s[4:5], -1
	v_lshl_add_u32 v152, s3, 6, v0
	s_ashr_i32 s3, s2, 31
	s_and_b32 s3, s3, s24
	s_add_i32 s25, s3, s2
	v_readlane_b32 s2, v255, 46
	v_readlane_b32 s3, v255, 47
	s_and_b64 vcc, exec, s[2:3]
	s_cbranch_vccz .LBB0_152
	v_mov_b32_e32 v130, v152
	s_cmpk_gt_i32 s25, 0x2bf
	v_readfirstlane_b32 s4, v130
	s_cbranch_scc1 .LBB0_151
	v_mov_b32_e32 v2, v1
	v_mov_b32_e32 v3, v1
	v_mov_b32_e32 v0, v1
	v_mov_b64_e32 v[12:13], v[2:3]
	v_mov_b64_e32 v[10:11], v[0:1]
	s_lshl_b64 s[2:3], s[56:57], 12
	s_add_u32 s48, s0, s2
	s_nop 0
	s_addc_u32 s2, s1, s3
	v_readlane_b32 s3, v255, 45
	s_nop 0
	s_mul_i32 s3, s3, 0x2c00000
	s_add_u32 s3, s12, s3
	s_nop 0
	s_addc_u32 s5, s13, 0
	s_add_u32 s8, s3, 0x200000
	s_nop 0
	s_addc_u32 s3, s5, 0
	s_ashr_i32 s5, s4, 6
	s_nop 0
	s_lshl_b32 s9, s5, 3
	v_bfe_u32 v2, v130, 3, 3
	s_nop 0
	v_or_b32_e32 v4, s9, v2
	v_and_b32_e32 v0, 63, v130
	s_nop 0
	v_lshrrev_b32_e32 v5, 1, v4
	s_lshl_b32 s10, s5, 1
	s_nop 0
	v_bfe_u32 v3, v0, 3, 2
	v_xor_b32_e32 v5, v5, v130
	s_nop 0
	v_lshlrev_b32_e32 v6, 1, v4
	v_and_or_b32 v3, s10, 4, v3
	s_nop 0
	v_lshlrev_b32_e32 v5, 4, v5
	s_and_b32 s10, s9, 0xfffe0
	s_nop 0
	v_and_b32_e32 v6, 24, v6
	s_add_i32 s9, s9, 64
	s_nop 0
	s_and_b32 s49, s2, 0xffff
	s_ashr_i32 s2, s25, 31
	v_and_b32_e32 v5, 0x70, v5
	v_or3_b32 v6, s10, v6, v3
	v_or_b32_e32 v2, s9, v2
	s_nop 0
	s_lshr_b32 s14, s2, 29
	v_lshl_or_b32 v153, v4, 12, v5
	v_lshl_or_b32 v154, v6, 12, v5
	v_lshlrev_b32_e32 v5, 1, v2
	s_nop 0
	s_add_i32 s14, s25, s14
	s_and_b32 s9, s9, 0xfffe0
	v_and_b32_e32 v5, 24, v5
	s_nop 0
	s_ashr_i32 s15, s14, 3
	s_and_b32 s14, s14, -8
	s_ashr_i32 s20, s4, 8
	v_or3_b32 v3, s9, v5, v3
	s_nop 0
	s_and_b32 s9, s3, 0xffff
	s_lshl_b32 s3, s5, 10
	s_sub_i32 s14, s25, s14
	s_nop 0
	s_cmp_lt_i32 s14, 0
	s_movk_i32 s16, 0x59
	s_nop 0
	s_cselect_b32 s16, s16, 0x58
	s_mul_i32 s14, s14, s16
	s_nop 0
	v_lshrrev_b32_e32 v4, 1, v2
	s_add_i32 s14, s14, s15
	s_nop 0
	v_xor_b32_e32 v4, v4, v130
	s_mul_hi_i32 s15, s14, 0x2e8ba2e9
	s_nop 0
	v_lshlrev_b32_e32 v4, 4, v4
	s_lshr_b32 s16, s15, 31
	s_nop 0
	s_ashr_i32 s15, s15, 5
	v_and_b32_e32 v4, 0x70, v4
	s_nop 0
	s_add_i32 s15, s15, s16
	v_lshl_or_b32 v155, v2, 12, v4
	v_lshl_or_b32 v156, v3, 12, v4
	s_nop 0
	s_lshl_b32 s16, s15, 2
	s_mulk_i32 s15, 0xb0
	s_nop 0
	s_sub_i32 s14, s14, s15
	s_bfe_u32 s15, s14, 0x2001d
	s_nop 0
	s_add_i32 s15, s14, s15
	s_sext_i32_i16 s17, s15
	s_nop 0
	s_add_i32 s3, s3, 0
	s_and_b32 s15, s15, 0xfffc
	s_nop 0
	s_ashr_i32 s53, s17, 2
	s_add_i32 s26, s3, 0x10000
	s_nop 0
	s_mov_b32 s10, s50
	s_mov_b32 s11, s51
	s_sub_i32 s14, s14, s15
	s_nop 0
	s_lshl_b32 s60, s53, 20
	s_mov_b32 m0, s26
	s_add_i32 s27, s3, 0x12000
	s_sext_i32_i16 s14, s14
	s_nop 0
	buffer_load_dwordx4 v154, s[8:11], s60 offen lds
	s_mov_b32 m0, s27
	s_add_i32 s28, s3, 0x14000
	s_add_i32 s58, s16, s14
	buffer_load_dwordx4 v156, s[8:11], s60 offen lds
	s_or_b32 s14, s60, 0x80000
	s_mov_b32 m0, s28
	s_add_i32 s29, s3, 0x16000
	buffer_load_dwordx4 v154, s[8:11], s14 offen lds
	s_mov_b32 m0, s29
	s_lshl_b32 s61, s58, 20
	buffer_load_dwordx4 v156, s[8:11], s14 offen lds
	s_waitcnt vmcnt(4)
	s_barrier
	s_mov_b32 m0, s3
	s_add_i32 s30, s3, 0x2000
	buffer_load_dwordx4 v153, s[48:51], s61 offen lds
	s_mov_b32 m0, s30
	s_add_i32 s31, s3, 0x4000
	buffer_load_dwordx4 v155, s[48:51], s61 offen lds
	s_or_b32 s10, s61, 0x80000
	s_mov_b32 m0, s31
	s_add_i32 s34, s3, 0x6000
	buffer_load_dwordx4 v153, s[48:51], s10 offen lds
	s_mov_b32 m0, s34
	s_nop 0
	buffer_load_dwordx4 v155, s[48:51], s10 offen lds
	s_cmp_eq_u32 s20, 1
	s_cselect_b64 s[14:15], -1, 0
	s_cmp_lg_u32 s20, 1
	s_cbranch_scc1 .LBB0_136
	s_barrier

.LBB0_152:
	s_andn2_b64 vcc, exec, s[4:5]
	s_cbranch_vccnz .LBB0_171
	s_cmp_ge_i32 s25, s74
	v_readfirstlane_b32 s4, v152
	s_cbranch_scc1 .LBB0_171
	v_readlane_b32 s2, v255, 40
	s_add_u32 s2, s12, s2
	s_addc_u32 s3, s13, 0
	s_add_u32 s5, s2, 0x21200000
	s_addc_u32 s9, s3, 0
	v_readlane_b32 s2, v255, 39
	s_add_u32 s2, s12, s2
	s_addc_u32 s3, s13, 0
	s_add_u32 s8, s2, 0x24600000
	s_addc_u32 s10, s3, 0
	v_readlane_b32 s2, v255, 31
	v_readlane_b32 s3, v255, 32
	s_and_b64 s[2:3], s[2:3], exec
	s_cselect_b32 s8, s5, s8
	s_cselect_b32 s9, s9, s10
	s_lshl_b64 s[2:3], s[56:57], 12
	s_add_u32 s48, s0, s2
	s_addc_u32 s0, s1, s3
	s_ashr_i32 s18, s4, 6
	v_and_b32_e32 v130, 63, v152
	s_lshl_b32 s1, s18, 3
	v_bfe_u32 v0, v152, 3, 3
	s_lshl_b32 s2, s18, 1
	v_bfe_u32 v2, v130, 3, 2
	v_and_or_b32 v4, s2, 4, v2
	v_or_b32_e32 v2, s1, v0
	v_lshrrev_b32_e32 v3, 1, v2
	s_and_b32 s49, s0, 0xffff
	s_ashr_i32 s0, s25, 31
	v_xor_b32_e32 v3, v3, v152
	v_lshlrev_b32_e32 v5, 1, v2
	s_lshr_b32 s3, s0, 29
	v_lshlrev_b32_e32 v3, 4, v3
	s_and_b32 s2, s1, 0xfffe0
	v_and_b32_e32 v5, 24, v5
	s_add_i32 s3, s25, s3
	v_and_b32_e32 v3, 0x70, v3
	v_or3_b32 v5, s2, v5, v4
	s_add_i32 s1, s1, 64
	s_ashr_i32 s10, s3, 3
	s_and_b32 s3, s3, -8
	s_ashr_i32 s5, s4, 8
	v_lshl_or_b32 v153, v5, 12, v3
	v_or_b32_e32 v5, s1, v0
	s_and_b32 s2, s1, 0xfffe0
	s_and_b32 s9, s9, 0xffff
	s_lshl_b32 s1, s18, 10
	s_sub_i32 s3, s25, s3
	s_cmp_lt_i32 s3, 0
	v_readlane_b32 s11, v255, 35
	v_readlane_b32 s14, v255, 36
	s_cselect_b32 s11, s14, s11
	s_mul_i32 s3, s3, s11
	s_add_i32 s3, s3, s10
	s_ashr_i32 s10, s3, 31
	v_readlane_b32 s11, v255, 43
	s_xor_b32 s10, s10, s11
	s_abs_i32 s11, s3
	v_readlane_b32 s14, v255, 44
	s_mul_hi_u32 s14, s11, s14
	s_mul_i32 s15, s14, s79
	s_sub_i32 s11, s11, s15
	s_add_i32 s15, s14, 1
	s_sub_i32 s16, s11, s79
	s_cmp_ge_u32 s11, s79
	s_cselect_b32 s14, s15, s14
	s_cselect_b32 s11, s16, s11
	s_add_i32 s15, s14, 1
	s_cmp_ge_u32 s11, s79
	s_cselect_b32 s11, s15, s14
	s_xor_b32 s11, s11, s10
	v_lshrrev_b32_e32 v0, 1, v5
	s_sub_i32 s14, s11, s10
	v_xor_b32_e32 v0, v0, v152
	s_lshl_b32 s15, s14, 2
	v_lshlrev_b32_e32 v0, 4, v0
	s_sub_i32 s10, 16, s15
	v_lshl_or_b32 v151, v2, 12, v3
	v_and_b32_e32 v6, 0x70, v0
	v_lshlrev_b32_e32 v0, 1, v5
	v_mov_b32_e32 v2, v1
	v_mov_b32_e32 v3, v1
	s_min_i32 s16, s10, 4
	v_and_b32_e32 v7, 24, v0
	v_mov_b32_e32 v0, v1
	v_mov_b64_e32 v[52:53], v[2:3]
	s_abs_i32 s17, s16
	v_mov_b64_e32 v[50:51], v[0:1]
	v_cvt_f32_u32_e32 v0, s17
	v_or3_b32 v2, s2, v7, v4
	s_nop 0
	v_rcp_iflag_f32_e32 v0, v0
	v_readlane_b32 s19, v255, 42
	s_nop 0
	v_mul_f32_e32 v0, 0x4f7ffffe, v0
	v_cvt_u32_f32_e32 v0, v0
	s_nop 0
	s_sub_i32 s20, 0, s17
	v_readfirstlane_b32 s2, v0
	s_nop 0
	s_mul_i32 s14, s14, s19
	s_mul_i32 s20, s20, s2
	s_nop 0
	s_sub_i32 s3, s3, s14
	s_mul_hi_u32 s20, s2, s20
	s_nop 0
	s_abs_i32 s19, s3
	s_add_i32 s2, s2, s20
	s_nop 0
	s_mul_hi_u32 s2, s19, s2
	s_mul_i32 s20, s2, s17
	s_nop 0
	s_xor_b32 s14, s3, s16
	s_sub_i32 s19, s19, s20
	s_nop 0
	s_ashr_i32 s14, s14, 31
	s_add_i32 s20, s2, 1
	s_nop 0
	s_sub_i32 s21, s19, s17
	s_cmp_ge_u32 s19, s17
	s_nop 0
	s_cselect_b32 s2, s20, s2
	s_cselect_b32 s19, s21, s19
	s_nop 0
	s_add_i32 s20, s2, 1
	v_lshl_or_b32 v155, v5, 12, v6
	s_nop 0
	v_lshl_or_b32 v156, v2, 12, v6
	s_cmp_ge_u32 s19, s17
	s_nop 0
	s_cselect_b32 s2, s20, s2
	s_xor_b32 s2, s2, s14
	s_nop 0
	s_sub_i32 s45, s2, s14
	s_mul_i32 s2, s45, s16
	s_nop 0
	s_sub_i32 s2, s3, s2
	s_add_i32 s1, s1, 0
	s_nop 0
	s_add_i32 s52, s2, s15
	s_add_i32 s2, s1, 0x10000
	s_nop 0
	s_mov_b32 s10, s50
	s_mov_b32 s11, s51
	s_nop 0
	s_lshl_b32 s53, s45, 20
	s_mov_b32 m0, s2
	s_nop 0
	s_add_i32 s3, s1, 0x12000
	s_add_i32 s20, s1, 0x14000
	s_nop 0
	s_or_b32 s14, s53, 0x80000
	s_add_i32 s21, s1, 0x16000
	s_nop 0
	s_lshl_b32 s54, s52, 20
	s_add_i32 s26, s1, 0x2000
	s_nop 0
	s_add_i32 s27, s1, 0x4000
	s_add_i32 s28, s1, 0x6000
	s_nop 0
	s_nop 0
	s_nop 0
	s_nop 0
	s_nop 0
	s_nop 0
	s_nop 0
	s_nop 0
	s_nop 0
	s_nop 0
	s_nop 0
	s_nop 0
	s_nop 0
	s_nop 0
	s_nop 0
	buffer_load_dwordx4 v153, s[8:11], s53 offen lds
	s_mov_b32 m0, s3
	s_nop 0
	buffer_load_dwordx4 v156, s[8:11], s53 offen lds
	s_mov_b32 m0, s20
	s_nop 0
	buffer_load_dwordx4 v153, s[8:11], s14 offen lds
	s_mov_b32 m0, s21
	s_nop 0
	buffer_load_dwordx4 v156, s[8:11], s14 offen lds
	s_waitcnt vmcnt(4)
	s_barrier
	s_mov_b32 m0, s1
	s_or_b32 s10, s54, 0x80000
	buffer_load_dwordx4 v151, s[48:51], s54 offen lds
	s_mov_b32 m0, s26
	s_cmp_eq_u32 s5, 1
	buffer_load_dwordx4 v155, s[48:51], s54 offen lds
	s_mov_b32 m0, s27
	s_cselect_b64 s[14:15], -1, 0
	buffer_load_dwordx4 v151, s[48:51], s10 offen lds
	s_mov_b32 m0, s28
	s_cmp_lg_u32 s5, 1
	buffer_load_dwordx4 v155, s[48:51], s10 offen lds
	s_cbranch_scc1 .LBB0_156
	s_barrier

.LBB0_355:
	s_or_b64 exec, exec, s[10:11]
	s_waitcnt vmcnt(0)
	buffer_inv sc1
.LBB0_356:
	s_or_b64 exec, exec, s[6:7]

.LBB0_369:
	s_xor_b64 s[12:13], s[8:9], -1
	s_andn2_b64 vcc, exec, s[10:11]
	s_cbranch_vccnz .LBB0_407
	v_mov_b32_e32 v2, v1
	v_mov_b32_e32 v3, v1
	v_mov_b32_e32 v0, v1
	v_mov_b64_e32 v[8:9], v[2:3]
	v_mov_b64_e32 v[6:7], v[0:1]
	s_add_u32 s8, s6, s2
	s_addc_u32 s9, s7, s1
	s_nop 0
	s_add_u32 s8, s8, s14
	s_addc_u32 s9, s9, 0
	s_nop 0
	s_ashr_i32 s24, s21, 6
	s_lshl_b32 s10, s24, 3
	s_nop 0
	v_bfe_u32 v10, v4, 3, 3
	v_or_b32_e32 v12, s10, v10
	s_nop 0
	v_lshrrev_b32_e32 v13, 1, v12
	v_and_b32_e32 v5, 63, v4
	s_nop 0
	v_xor_b32_e32 v13, v13, v4
	s_lshl_b32 s11, s24, 1
	s_nop 0
	v_bfe_u32 v11, v5, 3, 2
	v_lshlrev_b32_e32 v13, 3, v13
	s_nop 0
	v_lshlrev_b32_e32 v14, 1, v12
	v_and_or_b32 v11, s11, 4, v11
	s_nop 0
	v_and_b32_e32 v13, 56, v13
	s_and_b32 s11, s10, 0x7fffffe0
	s_nop 0
	v_and_b32_e32 v14, 24, v14
	v_mul_lo_u32 v12, v12, s20
	s_nop 0
	v_or3_b32 v14, s11, v14, v11
	v_or_b32_e32 v12, v13, v12
	s_nop 0
	v_lshlrev_b32_e32 v204, 1, v12
	v_mul_lo_u32 v12, v14, s20
	s_nop 0
	s_add_i32 s10, s10, 64
	v_or_b32_e32 v12, v12, v13
	s_nop 0
	v_or_b32_e32 v10, s10, v10
	v_lshlrev_b32_e32 v205, 1, v12
	s_nop 0
	v_lshrrev_b32_e32 v12, 1, v10
	v_xor_b32_e32 v12, v12, v4
	s_nop 0
	v_lshlrev_b32_e32 v12, 3, v12
	v_lshlrev_b32_e32 v13, 1, v10
	s_nop 0
	v_and_b32_e32 v12, 56, v12
	s_and_b32 s10, s10, 0x7fffffe0
	s_nop 0
	v_and_b32_e32 v13, 24, v13
	v_mul_lo_u32 v10, v10, s20
	s_nop 0
	s_lshl_b32 s14, s24, 10
	v_or3_b32 v11, s10, v13, v11
	s_nop 0
	v_or_b32_e32 v10, v12, v10
	s_add_i32 s31, s14, 0
	s_nop 0
	v_lshlrev_b32_e32 v206, 1, v10
	v_mul_lo_u32 v10, v11, s20
	s_nop 0
	s_lshl_b32 s30, s20, 9
	s_add_i32 s34, s31, 0x10000
	s_nop 0
	v_or_b32_e32 v10, v10, v12
	s_and_b32 s9, s9, 0xffff
	s_nop 0
	s_mov_b32 s10, s50
	s_mov_b32 s11, s51
	s_nop 0
	s_mul_i32 s65, s23, s30
	s_mov_b32 m0, s34
	s_nop 0
	s_add_i32 s35, s31, 0x12000
	v_lshlrev_b32_e32 v207, 1, v10
	s_nop 0
	s_lshl_b32 s29, s20, 8
	s_add_i32 s36, s31, 0x14000
	s_nop 0
	s_add_i32 s46, s65, s29
	s_add_i32 s37, s31, 0x16000
	s_nop 0
	s_and_b32 s49, s49, 0xffff
	s_mul_i32 s64, s22, s30
	s_nop 0
	s_add_i32 s38, s31, 0x2000
	s_add_i32 s39, s31, 0x4000
	s_nop 0
	s_add_i32 s40, s31, 0x6000
	s_ashr_i32 s25, s21, 8
	s_nop 0
	buffer_load_dwordx4 v205, s[8:11], s65 offen lds
	s_mov_b32 m0, s35
	s_nop 0
	buffer_load_dwordx4 v207, s[8:11], s65 offen lds
	s_mov_b32 m0, s36
	s_nop 0
	buffer_load_dwordx4 v205, s[8:11], s46 offen lds
	s_mov_b32 m0, s37
	s_nop 0
	buffer_load_dwordx4 v207, s[8:11], s46 offen lds
	s_waitcnt vmcnt(4)
	s_barrier
	s_mov_b32 m0, s31
	s_add_i32 s10, s64, s29
	buffer_load_dwordx4 v204, s[48:51], s64 offen lds
	s_mov_b32 m0, s38
	s_cmp_eq_u32 s25, 1
	buffer_load_dwordx4 v206, s[48:51], s64 offen lds
	s_mov_b32 m0, s39
	s_cselect_b64 s[14:15], -1, 0
	buffer_load_dwordx4 v204, s[48:51], s10 offen lds
	s_mov_b32 m0, s40
	s_cmp_lg_u32 s25, 1
	buffer_load_dwordx4 v206, s[48:51], s10 offen lds
	s_cbranch_scc1 .LBB0_372
	s_barrier
